# diff-attn PV: second batch of V fragment reads issued before the first batch's MFMAs (own registers)
# speedup vs baseline: 1.0004x; 1.0004x over previous
.LBB0_629:
	v_add_u32_e32 v0, s26, v125
	v_add3_u32 v147, v0, v130, v131
	v_add3_u32 v165, v0, v130, v133
	v_add3_u32 v166, v0, v130, v140
	v_add3_u32 v167, v0, v130, v141
	v_add3_u32 v168, v0, v130, v142
	v_add3_u32 v169, v0, v130, v143
	v_add3_u32 v170, v0, v130, v144
	v_add3_u32 v0, v0, v130, v145
	ds_read_b64_tr_b16 v[82:83], v147
	ds_read_b64_tr_b16 v[84:85], v165 offset:2048
	ds_read_b64_tr_b16 v[86:87], v147 offset:4096
	ds_read_b64_tr_b16 v[88:89], v165 offset:6144
	ds_read_b64_tr_b16 v[90:91], v147 offset:8192
	ds_read_b64_tr_b16 v[92:93], v165 offset:10240
	ds_read_b64_tr_b16 v[94:95], v147 offset:12288
	ds_read_b64_tr_b16 v[96:97], v165 offset:14336
	ds_read_b64_tr_b16 v[148:149], v166
	ds_read_b64_tr_b16 v[150:151], v167 offset:2048
	ds_read_b64_tr_b16 v[152:153], v166 offset:4096
	ds_read_b64_tr_b16 v[154:155], v167 offset:6144
	ds_read_b64_tr_b16 v[156:157], v166 offset:8192
	ds_read_b64_tr_b16 v[158:159], v167 offset:10240
	ds_read_b64_tr_b16 v[160:161], v166 offset:12288
	ds_read_b64_tr_b16 v[162:163], v167 offset:14336
	s_waitcnt lgkmcnt(0)
	s_nop 0
	ds_read_b64_tr_b16 v[176:177], v168
	ds_read_b64_tr_b16 v[178:179], v169 offset:2048
	ds_read_b64_tr_b16 v[180:181], v168 offset:4096
	ds_read_b64_tr_b16 v[182:183], v169 offset:6144
	ds_read_b64_tr_b16 v[184:185], v168 offset:8192
	ds_read_b64_tr_b16 v[186:187], v169 offset:10240
	ds_read_b64_tr_b16 v[188:189], v168 offset:12288
	ds_read_b64_tr_b16 v[190:191], v169 offset:14336
	ds_read_b64_tr_b16 v[192:193], v170
	ds_read_b64_tr_b16 v[194:195], v0 offset:2048
	ds_read_b64_tr_b16 v[196:197], v170 offset:4096
	ds_read_b64_tr_b16 v[198:199], v0 offset:6144
	ds_read_b64_tr_b16 v[216:217], v170 offset:8192
	ds_read_b64_tr_b16 v[218:219], v0 offset:10240
	ds_read_b64_tr_b16 v[220:221], v170 offset:12288
	ds_read_b64_tr_b16 v[222:223], v0 offset:14336
	v_mfma_f32_32x32x16_bf16 v[50:65], v[82:85], v[74:77], v[50:65]
	v_mfma_f32_32x32x16_bf16 v[34:49], v[148:151], v[74:77], v[34:49]
	v_mfma_f32_32x32x16_bf16 v[50:65], v[86:89], v[78:81], v[50:65]
	v_mfma_f32_32x32x16_bf16 v[34:49], v[152:155], v[78:81], v[34:49]
	v_mfma_f32_32x32x16_bf16 v[50:65], v[90:93], v[66:69], v[50:65]
	v_mfma_f32_32x32x16_bf16 v[34:49], v[156:159], v[66:69], v[34:49]
	v_mfma_f32_32x32x16_bf16 v[50:65], v[94:97], v[70:73], v[50:65]
	v_mfma_f32_32x32x16_bf16 v[34:49], v[160:163], v[70:73], v[34:49]
	s_waitcnt lgkmcnt(0)
	v_mfma_f32_32x32x16_bf16 v[18:33], v[176:179], v[74:77], v[18:33]
	v_mfma_f32_32x32x16_bf16 v[2:17], v[192:195], v[74:77], v[2:17]
	v_mfma_f32_32x32x16_bf16 v[18:33], v[180:183], v[78:81], v[18:33]
	v_mfma_f32_32x32x16_bf16 v[2:17], v[196:199], v[78:81], v[2:17]
	v_mfma_f32_32x32x16_bf16 v[18:33], v[184:187], v[66:69], v[18:33]
	v_mfma_f32_32x32x16_bf16 v[2:17], v[216:219], v[66:69], v[2:17]
	v_mfma_f32_32x32x16_bf16 v[18:33], v[188:191], v[70:73], v[18:33]
	v_mfma_f32_32x32x16_bf16 v[2:17], v[220:223], v[70:73], v[2:17]
	v_mov_b32_e32 v147, v164
	s_andn2_b64 vcc, exec, s[2:3]
	s_mov_b64 s[2:3], -1
	s_cbranch_vccz .LBB0_631
	s_branch .LBB0_632
